# one static priority raise (s_setprio 1 at kernel start) for waves 4-7, the trailing half of the 8-phase GEMM; per-segment toggles removed
# baseline (speedup 1.0000x reference)
; template <class Epi, class Sched, bool ALIGN_EPI = false, bool SP2 = false>
; __device__ __forceinline__ void gemm_phase(PG8_LAS unsigned char* lds, const Gemm g, const Sched& S, const Epi& E) {
;     const int tid = threadIdx.x, wid = __builtin_amdgcn_readfirstlane(tid >> 6), lane = tid & 63, wr = wid >> 2, wc = wid & 3, fr = lane & 15, fq = lane >> 4;
.LBB0_17:
	v_readfirstlane_b32 s98, v254
	s_bitcmp1_b32 s98, 8
	s_cbranch_scc0 .Lprio_skip
	s_setprio 1
